# speedup vs baseline: 1.0361x; 1.0156x over previous
.LBB0_572:
	s_waitcnt lgkmcnt(0)
	v_mfma_f32_32x32x16_bf16 v[80:95], v[112:115], v[96:99], 0
	s_add_i32 s10, s12, 4
	s_cmp_ge_u32 s10, s19
	s_cbranch_scc1 .Lda_sk1
	s_and_b32 s10, s10, 3
	s_mulk_i32 s10, 0x5000
	s_add_i32 s10, s14, s10
	s_mov_b32 m0, s10
	s_nop 0
	global_load_lds_dwordx4 v[180:181], off
.Lda_sk1:
	s_and_b64 vcc, exec, s[2:3]
	v_mfma_f32_32x32x16_bf16 v[64:79], v[116:119], v[96:99], 0
	v_mfma_f32_32x32x16_bf16 v[80:95], v[120:123], v[100:103], v[80:95]
	s_add_i32 s13, s12, 4
	s_cmp_ge_u32 s13, s19
	s_cbranch_scc1 .Lda_sk2
	s_add_i32 m0, s10, 0x3000
	s_nop 0
	global_load_lds_dwordx4 v[178:179], off
.Lda_sk2:
	v_mfma_f32_32x32x16_bf16 v[64:79], v[124:127], v[100:103], v[64:79]
	s_cbranch_vccnz .Lda_anym0

.LBB0_647:
	s_waitcnt lgkmcnt(0)
	v_mfma_f32_32x32x16_bf16 v[48:63], v[108:111], v[68:71], 0
	s_add_i32 s12, s7, 2
	s_cmp_ge_u32 s12, s19
	s_cbranch_scc1 .Lgq_sk1
	s_and_b32 s12, s12, 3
	s_mulk_i32 s12, 0x5000
	s_add_i32 s12, s5, s12
	s_mov_b32 m0, s12
	s_nop 0
	global_load_lds_dwordx4 v[148:149], off
.Lgq_sk1:
	s_andn2_b64 vcc, exec, s[2:3]
	v_mfma_f32_32x32x16_bf16 v[32:47], v[104:107], v[68:71], 0
	v_mfma_f32_32x32x16_bf16 v[48:63], v[100:103], v[64:67], v[48:63]
	s_add_i32 s13, s7, 2
	s_cmp_ge_u32 s13, s19
	s_cbranch_scc1 .Lgq_sk2
	s_add_i32 m0, s12, 0x3000
	s_nop 0
	global_load_lds_dwordx4 v[150:151], off
.Lgq_sk2:
	v_mfma_f32_32x32x16_bf16 v[32:47], v[96:99], v[64:67], v[32:47]
	v_mfma_f32_32x32x16_bf16 v[48:63], v[92:95], v[76:79], v[48:63]
	v_mfma_f32_32x32x16_bf16 v[32:47], v[88:91], v[76:79], v[32:47]
	v_mfma_f32_32x32x16_bf16 v[48:63], v[84:87], v[72:75], v[48:63]
	v_mfma_f32_32x32x16_bf16 v[32:47], v[80:83], v[72:75], v[32:47]
	s_cbranch_vccz .Lgq_anym

.LBB0_680:
	s_waitcnt lgkmcnt(0)
	v_mfma_f32_32x32x16_bf16 v[32:47], v[116:119], v[84:87], 0
	s_cmp_ge_u32 s7, s19
	s_cbranch_scc1 .Lml_sk1
	s_and_b32 s16, s7, 3
	s_mulk_i32 s16, 0x5000
	s_add_i32 s16, s5, s16
	s_mov_b32 m0, s16
	s_and_b64 vcc, exec, s[10:11]
	global_load_lds_dwordx4 v[172:173], off
.Lml_sk1:
	s_add_i32 s14, s7, -3
	s_and_b32 s14, s14, 3
	s_mulk_i32 s14, 0x5000
	v_add_u32_e32 v116, s14, v186
	v_mfma_f32_32x32x16_bf16 v[32:47], v[112:115], v[80:83], v[32:47]
	v_mfma_f32_32x32x16_bf16 v[48:63], v[108:111], v[84:87], 0
	s_cmp_ge_u32 s7, s19
	s_cbranch_scc1 .Lml_sk2
	s_add_i32 m0, s16, 0x3000
	s_nop 0
	global_load_lds_dwordx4 v[156:157], off
	s_cbranch_vccnz .Lml_sk2
	s_add_i32 m0, s16, 0x2000
	s_nop 0
	global_load_lds_dwordx4 v[158:159], off
.Lml_sk2:
	v_add_u32_e32 v193, v116, v190
	v_add_u32_e32 v192, v116, v191
	ds_read_b128 v[108:111], v193 offset:8192
	ds_read_b128 v[112:115], v193 offset:10240
	ds_read_b128 v[116:119], v192 offset:8192
	ds_read_b128 v[120:123], v192 offset:10240
	v_mfma_f32_32x32x16_bf16 v[48:63], v[104:107], v[80:83], v[48:63]
	v_mfma_f32_32x32x16_bf16 v[32:47], v[100:103], v[76:79], v[32:47]
	s_andn2_b64 vcc, exec, s[12:13]
	v_mfma_f32_32x32x16_bf16 v[48:63], v[96:99], v[76:79], v[48:63]
	v_mfma_f32_32x32x16_bf16 v[32:47], v[92:95], v[72:75], v[32:47]
	v_mfma_f32_32x32x16_bf16 v[48:63], v[88:91], v[72:75], v[48:63]
	s_waitcnt lgkmcnt(0)
	v_mfma_f32_32x32x16_bf16 v[32:47], v[108:111], v[68:71], v[32:47]
	v_mfma_f32_32x32x16_bf16 v[48:63], v[112:115], v[68:71], v[48:63]
	v_mfma_f32_32x32x16_bf16 v[32:47], v[116:119], v[64:67], v[32:47]
	v_mfma_f32_32x32x16_bf16 v[48:63], v[120:123], v[64:67], v[48:63]
	s_cbranch_vccz .Lml_anym
